# phase-5 worker tail converts next-layer W1B/WIN; phase-1 slot WG/WBR/WO/W2A; phase-10 slot W2B + next-layer W1A/WKV/small/LV; phase 0 (and its barrier) only for layer 0
# speedup vs baseline: 1.0048x; 1.0002x over previous
; #define LAS __attribute__((address_space(3)))
; __device__ __forceinline__ f32x4 mfma16(bf16x8 a, bf16x8 b, f32x4 c) { return __builtin_amdgcn_mfma_f32_16x16x32_bf16(a, b, c, 0, 0, 0); }
; __device__ __forceinline__ void xa_pair(LAS unsigned char* lds, const bf16_t* Ux, const bf16_t* Kb, const bf16_t* Vt, bf16_t* Yx, int pair, int tid) {
;     ...
;         const int t = b * SEQ + (blk0 + tq) * 128 + 16 * wave + fr;
;         bf16x8 qf[4];
; #pragma unroll
;         for (int ks = 0; ks < 4; ++ks) qf[ks] = *(const bf16x8*)(Ux + (size_t)t * 512 + h * 128 + ks * 32 + fq * 8);
;         f32x4 s[16];
; #pragma unroll
;         for (int nt = 0; nt < 16; ++nt) { s[nt] = (f32x4){0.f, 0.f, 0.f, 0.f}; LAS const unsigned char* kr = lds + (16 * nt + fr) * XK_STRIDE + fq * 16;
; #pragma unroll
;             for (int ks = 0; ks < 4; ++ks) s[nt] = mfma16(*(LAS const bf16x8*)(kr + ks * 64), qf[ks], s[nt]);
;             if (nt & 1) asm volatile("" ::: "memory"); }
.LBB0_318:
	v_add_u32_e32 v2, s8, v136
	v_ashrrev_i32_e32 v3, 31, v2
	v_lshlrev_b64 v[114:115], 10, v[2:3]
	v_lshl_add_u64 v[2:3], v[110:111], 0, v[114:115]
	global_load_dwordx4 v[74:77], v[2:3], off
	global_load_dwordx4 v[70:73], v[2:3], off offset:64
	global_load_dwordx4 v[66:69], v[2:3], off offset:128
	global_load_dwordx4 v[54:57], v[2:3], off offset:192
	s_mov_b32 s8, 0xf149f2ca
	ds_read_b128 v[164:167], v134
	ds_read_b128 v[168:171], v134 offset:64
	ds_read_b128 v[172:175], v134 offset:128
	ds_read_b128 v[176:179], v134 offset:192
	ds_read_b128 v[180:183], v134 offset:4352
	ds_read_b128 v[184:187], v134 offset:4416
	ds_read_b128 v[188:191], v134 offset:4480
	ds_read_b128 v[192:195], v134 offset:4544
	ds_read_b128 v[196:199], v134 offset:8704
	ds_read_b128 v[200:203], v134 offset:8768
	ds_read_b128 v[204:207], v134 offset:8832
	ds_read_b128 v[212:215], v134 offset:8896
	s_waitcnt vmcnt(0)
	s_waitcnt lgkmcnt(8)
	v_mfma_f32_16x16x32_bf16 v[58:61], v[164:167], v[74:77], 0
	v_mfma_f32_16x16x32_bf16 v[58:61], v[168:171], v[70:73], v[58:61]
	v_mfma_f32_16x16x32_bf16 v[58:61], v[172:175], v[66:69], v[58:61]
	v_mfma_f32_16x16x32_bf16 v[58:61], v[176:179], v[54:57], v[58:61]
	ds_read_b128 v[164:167], v134 offset:13056
	ds_read_b128 v[168:171], v134 offset:13120
	ds_read_b128 v[172:175], v134 offset:13184
	ds_read_b128 v[176:179], v134 offset:13248
	s_waitcnt lgkmcnt(8)
	v_mfma_f32_16x16x32_bf16 v[46:49], v[180:183], v[74:77], 0
	v_mfma_f32_16x16x32_bf16 v[46:49], v[184:187], v[70:73], v[46:49]
	v_mfma_f32_16x16x32_bf16 v[46:49], v[188:191], v[66:69], v[46:49]
	v_mfma_f32_16x16x32_bf16 v[46:49], v[192:195], v[54:57], v[46:49]
	ds_read_b128 v[180:183], v134 offset:17408
	ds_read_b128 v[184:187], v134 offset:17472
	ds_read_b128 v[188:191], v134 offset:17536
	ds_read_b128 v[192:195], v134 offset:17600
	s_waitcnt lgkmcnt(8)
	v_mfma_f32_16x16x32_bf16 v[62:65], v[196:199], v[74:77], 0
	v_mfma_f32_16x16x32_bf16 v[62:65], v[200:203], v[70:73], v[62:65]
	v_mfma_f32_16x16x32_bf16 v[62:65], v[204:207], v[66:69], v[62:65]
	v_mfma_f32_16x16x32_bf16 v[62:65], v[212:215], v[54:57], v[62:65]
	ds_read_b128 v[196:199], v134 offset:21760
	ds_read_b128 v[200:203], v134 offset:21824
	ds_read_b128 v[204:207], v134 offset:21888
	ds_read_b128 v[212:215], v134 offset:21952
	s_waitcnt lgkmcnt(8)
	v_mfma_f32_16x16x32_bf16 v[50:53], v[164:167], v[74:77], 0
	v_mfma_f32_16x16x32_bf16 v[50:53], v[168:171], v[70:73], v[50:53]
	v_mfma_f32_16x16x32_bf16 v[50:53], v[172:175], v[66:69], v[50:53]
	v_mfma_f32_16x16x32_bf16 v[50:53], v[176:179], v[54:57], v[50:53]
	ds_read_b128 v[164:167], v134 offset:26112
	ds_read_b128 v[168:171], v134 offset:26176
	ds_read_b128 v[172:175], v134 offset:26240
	ds_read_b128 v[176:179], v134 offset:26304
	s_waitcnt lgkmcnt(8)
	v_mfma_f32_16x16x32_bf16 v[42:45], v[180:183], v[74:77], 0
	v_mfma_f32_16x16x32_bf16 v[42:45], v[184:187], v[70:73], v[42:45]
	v_mfma_f32_16x16x32_bf16 v[42:45], v[188:191], v[66:69], v[42:45]
	v_mfma_f32_16x16x32_bf16 v[42:45], v[192:195], v[54:57], v[42:45]
	ds_read_b128 v[180:183], v134 offset:30464
	ds_read_b128 v[184:187], v134 offset:30528
	ds_read_b128 v[188:191], v134 offset:30592
	ds_read_b128 v[192:195], v134 offset:30656
	s_waitcnt lgkmcnt(8)
	v_mfma_f32_16x16x32_bf16 v[38:41], v[196:199], v[74:77], 0
	v_mfma_f32_16x16x32_bf16 v[38:41], v[200:203], v[70:73], v[38:41]
	v_mfma_f32_16x16x32_bf16 v[38:41], v[204:207], v[66:69], v[38:41]
	v_mfma_f32_16x16x32_bf16 v[38:41], v[212:215], v[54:57], v[38:41]
	ds_read_b128 v[196:199], v134 offset:34816
	ds_read_b128 v[200:203], v134 offset:34880
	ds_read_b128 v[204:207], v134 offset:34944
	ds_read_b128 v[212:215], v134 offset:35008
	s_waitcnt lgkmcnt(8)
	v_mfma_f32_16x16x32_bf16 v[34:37], v[164:167], v[74:77], 0
	v_mfma_f32_16x16x32_bf16 v[34:37], v[168:171], v[70:73], v[34:37]
	v_mfma_f32_16x16x32_bf16 v[34:37], v[172:175], v[66:69], v[34:37]
	v_mfma_f32_16x16x32_bf16 v[34:37], v[176:179], v[54:57], v[34:37]
	ds_read_b128 v[164:167], v134 offset:39168
	ds_read_b128 v[168:171], v134 offset:39232
	ds_read_b128 v[172:175], v134 offset:39296
	ds_read_b128 v[176:179], v134 offset:39360
	s_waitcnt lgkmcnt(8)
	v_mfma_f32_16x16x32_bf16 v[30:33], v[180:183], v[74:77], 0
	v_mfma_f32_16x16x32_bf16 v[30:33], v[184:187], v[70:73], v[30:33]
	v_mfma_f32_16x16x32_bf16 v[30:33], v[188:191], v[66:69], v[30:33]
	v_mfma_f32_16x16x32_bf16 v[30:33], v[192:195], v[54:57], v[30:33]
	ds_read_b128 v[180:183], v134 offset:43520
	ds_read_b128 v[184:187], v134 offset:43584
	ds_read_b128 v[188:191], v134 offset:43648
	ds_read_b128 v[192:195], v134 offset:43712
	s_waitcnt lgkmcnt(8)
	v_mfma_f32_16x16x32_bf16 v[26:29], v[196:199], v[74:77], 0
	v_mfma_f32_16x16x32_bf16 v[26:29], v[200:203], v[70:73], v[26:29]
	v_mfma_f32_16x16x32_bf16 v[26:29], v[204:207], v[66:69], v[26:29]
	v_mfma_f32_16x16x32_bf16 v[26:29], v[212:215], v[54:57], v[26:29]
	ds_read_b128 v[196:199], v134 offset:47872
	ds_read_b128 v[200:203], v134 offset:47936
	ds_read_b128 v[204:207], v134 offset:48000
	ds_read_b128 v[212:215], v134 offset:48064
	s_waitcnt lgkmcnt(8)
	v_mfma_f32_16x16x32_bf16 v[22:25], v[164:167], v[74:77], 0
	v_mfma_f32_16x16x32_bf16 v[22:25], v[168:171], v[70:73], v[22:25]
	v_mfma_f32_16x16x32_bf16 v[22:25], v[172:175], v[66:69], v[22:25]
	v_mfma_f32_16x16x32_bf16 v[22:25], v[176:179], v[54:57], v[22:25]
	ds_read_b128 v[164:167], v134 offset:52224
	ds_read_b128 v[168:171], v134 offset:52288
	ds_read_b128 v[172:175], v134 offset:52352
	ds_read_b128 v[176:179], v134 offset:52416
	s_waitcnt lgkmcnt(8)
; #define LAS __attribute__((address_space(3)))
; __device__ __forceinline__ f32x4 mfma16(bf16x8 a, bf16x8 b, f32x4 c) { return __builtin_amdgcn_mfma_f32_16x16x32_bf16(a, b, c, 0, 0, 0); }
; __device__ __forceinline__ void xa_pair(LAS unsigned char* lds, const bf16_t* Ux, const bf16_t* Kb, const bf16_t* Vt, bf16_t* Yx, int pair, int tid) {
;     ...
;         for (int nt = 0; nt < 16; ++nt) { s[nt] = (f32x4){0.f, 0.f, 0.f, 0.f}; LAS const unsigned char* kr = lds + (16 * nt + fr) * XK_STRIDE + fq * 16;
; #pragma unroll
;             for (int ks = 0; ks < 4; ++ks) s[nt] = mfma16(*(LAS const bf16x8*)(kr + ks * 64), qf[ks], s[nt]);
;             if (nt & 1) asm volatile("" ::: "memory"); }
;         float mx = -1e30f;
; #pragma unroll
;         for (int nt = 0; nt < 16; ++nt)
; #pragma unroll
;             for (int j = 0; j < 4; ++j) mx = fmaxf(mx, s[nt][j]);
;         mx = fmaxf(mx, __shfl_xor(mx, 16)); mx = fmaxf(mx, __shfl_xor(mx, 32));
;         const float sc = 0.08838834764831845f * 1.4426950408889634f; float l = 0.f;
; #pragma unroll
;         for (int nt = 0; nt < 16; ++nt)
; #pragma unroll
;             for (int j = 0; j < 4; ++j) { const float pz = exp2f((s[nt][j] - mx) * sc); s[nt][j] = pz; l += pz; }
	v_mfma_f32_16x16x32_bf16 v[18:21], v[180:183], v[74:77], 0
	v_mfma_f32_16x16x32_bf16 v[18:21], v[184:187], v[70:73], v[18:21]
	v_mfma_f32_16x16x32_bf16 v[18:21], v[188:191], v[66:69], v[18:21]
	v_mfma_f32_16x16x32_bf16 v[18:21], v[192:195], v[54:57], v[18:21]
	ds_read_b128 v[180:183], v134 offset:56576
	ds_read_b128 v[184:187], v134 offset:56640
	ds_read_b128 v[188:191], v134 offset:56704
	ds_read_b128 v[192:195], v134 offset:56768
	s_waitcnt lgkmcnt(8)
	v_mfma_f32_16x16x32_bf16 v[10:13], v[196:199], v[74:77], 0
	v_mfma_f32_16x16x32_bf16 v[10:13], v[200:203], v[70:73], v[10:13]
	v_mfma_f32_16x16x32_bf16 v[10:13], v[204:207], v[66:69], v[10:13]
	v_mfma_f32_16x16x32_bf16 v[10:13], v[212:215], v[54:57], v[10:13]
	ds_read_b128 v[196:199], v134 offset:60928
	ds_read_b128 v[200:203], v134 offset:60992
	ds_read_b128 v[204:207], v134 offset:61056
	ds_read_b128 v[212:215], v134 offset:61120
	s_waitcnt lgkmcnt(8)
	v_mfma_f32_16x16x32_bf16 v[2:5], v[164:167], v[74:77], 0
	v_mfma_f32_16x16x32_bf16 v[2:5], v[168:171], v[70:73], v[2:5]
	v_mfma_f32_16x16x32_bf16 v[2:5], v[172:175], v[66:69], v[2:5]
	v_mfma_f32_16x16x32_bf16 v[2:5], v[176:179], v[54:57], v[2:5]
	ds_read_b128 v[164:167], v134 offset:65280
	ds_read_b128 v[168:171], v134 offset:65344
	ds_read_b128 v[172:175], v134 offset:65408
	ds_read_b128 v[176:179], v134 offset:65472
	s_waitcnt lgkmcnt(8)
	v_mfma_f32_16x16x32_bf16 v[14:17], v[180:183], v[74:77], 0
	v_mfma_f32_16x16x32_bf16 v[14:17], v[184:187], v[70:73], v[14:17]
	v_mfma_f32_16x16x32_bf16 v[14:17], v[188:191], v[66:69], v[14:17]
	v_mfma_f32_16x16x32_bf16 v[14:17], v[192:195], v[54:57], v[14:17]
	s_waitcnt lgkmcnt(4)
	v_mfma_f32_16x16x32_bf16 v[6:9], v[196:199], v[74:77], 0
	v_mfma_f32_16x16x32_bf16 v[6:9], v[200:203], v[70:73], v[6:9]
	v_mfma_f32_16x16x32_bf16 v[6:9], v[204:207], v[66:69], v[6:9]
	v_mfma_f32_16x16x32_bf16 v[6:9], v[212:215], v[54:57], v[6:9]
	s_waitcnt lgkmcnt(0)
	v_mfma_f32_16x16x32_bf16 v[216:219], v[164:167], v[74:77], 0
	v_mfma_f32_16x16x32_bf16 v[216:219], v[168:171], v[70:73], v[216:219]
	v_mfma_f32_16x16x32_bf16 v[216:219], v[172:175], v[66:69], v[216:219]
	v_mfma_f32_16x16x32_bf16 v[54:57], v[176:179], v[54:57], v[216:219]
	s_nop 7
	s_nop 2
	v_max3_f32 v66, v58, s8, v59
	v_max3_f32 v66, v66, v60, v61
	v_max3_f32 v66, v66, v46, v47
	v_max3_f32 v66, v66, v48, v49
	v_max3_f32 v66, v66, v62, v63
	v_max3_f32 v66, v66, v64, v65
	v_max3_f32 v66, v66, v50, v51
	v_max3_f32 v66, v66, v52, v53
	v_max3_f32 v66, v66, v42, v43
	v_max3_f32 v66, v66, v44, v45
	v_max3_f32 v66, v66, v38, v39
	v_max3_f32 v66, v66, v40, v41
	v_max3_f32 v66, v66, v34, v35
	v_max3_f32 v66, v66, v36, v37
	v_max3_f32 v66, v66, v30, v31
	v_max3_f32 v66, v66, v32, v33
	v_max3_f32 v66, v66, v26, v27
	v_max3_f32 v66, v66, v28, v29
	v_max3_f32 v66, v66, v22, v23
	v_max3_f32 v66, v66, v24, v25
	v_max3_f32 v66, v66, v18, v19
	v_max3_f32 v66, v66, v20, v21
	v_max3_f32 v66, v66, v10, v11
	v_max3_f32 v66, v66, v12, v13
	v_max3_f32 v66, v66, v2, v3
	v_max3_f32 v66, v66, v4, v5
	v_max3_f32 v66, v66, v14, v15
	v_max3_f32 v66, v66, v16, v17
	v_max3_f32 v66, v66, v6, v7
	v_max3_f32 v66, v66, v8, v9
	v_max3_f32 v66, v66, v54, v55
	v_max3_f32 v66, v66, v56, v57
	ds_bpermute_b32 v67, v124, v66
	s_waitcnt lgkmcnt(0)
	v_max_f32_e32 v67, v67, v67
	v_max_f32_e32 v66, v66, v67
	ds_bpermute_b32 v67, v125, v66
	s_waitcnt lgkmcnt(0)
	v_max_f32_e32 v67, v67, v67
	v_max_f32_e32 v140, v66, v67
	v_mov_b32_e32 v69, 0x3e0293ee
	v_mul_f32_e64 v67, -v140, v69
	v_mov_b32_e32 v220, v135
	v_add_u32_e32 v221, 0x2100, v135
	v_add_u32_e32 v222, 0x4200, v135
	v_add_u32_e32 v223, 0x6300, v135
	v_add_u32_e32 v224, 0x8400, v135
	v_add_u32_e32 v225, 0xa500, v135
	v_add_u32_e32 v226, 0xc600, v135
	v_add_u32_e32 v227, 0xe700, v135
	ds_read2_b64 v[164:167], v220 offset0:0 offset1:4
	ds_read2_b64 v[168:171], v221 offset0:0 offset1:4
	ds_read2_b64 v[172:175], v222 offset0:0 offset1:4
	ds_read2_b64 v[176:179], v223 offset0:0 offset1:4
	ds_read2_b64 v[180:183], v224 offset0:0 offset1:4
	ds_read2_b64 v[184:187], v225 offset0:0 offset1:4
	ds_read2_b64 v[188:191], v226 offset0:0 offset1:4
	ds_read2_b64 v[192:195], v227 offset0:0 offset1:4
	ds_read2_b64 v[196:199], v220 offset0:8 offset1:12
	ds_read2_b64 v[200:203], v221 offset0:8 offset1:12
	ds_read2_b64 v[204:207], v222 offset0:8 offset1:12
	ds_read2_b64 v[212:215], v223 offset0:8 offset1:12
	v_fma_f32 v58, v58, v69, v67
	v_fma_f32 v59, v59, v69, v67
	v_fma_f32 v60, v60, v69, v67
	v_fma_f32 v61, v61, v69, v67
	v_exp_f32_e32 v58, v58
	v_exp_f32_e32 v59, v59
	v_exp_f32_e32 v60, v60
	v_exp_f32_e32 v61, v61
	v_fma_f32 v46, v46, v69, v67
	v_fma_f32 v47, v47, v69, v67
	v_fma_f32 v48, v48, v69, v67
	v_fma_f32 v49, v49, v69, v67
	v_exp_f32_e32 v46, v46
	v_exp_f32_e32 v47, v47
	v_exp_f32_e32 v48, v48
	v_exp_f32_e32 v49, v49
	v_fma_f32 v62, v62, v69, v67
	v_fma_f32 v63, v63, v69, v67
	v_fma_f32 v64, v64, v69, v67
	v_fma_f32 v65, v65, v69, v67
	v_exp_f32_e32 v62, v62
	v_exp_f32_e32 v63, v63
	v_exp_f32_e32 v64, v64
	v_exp_f32_e32 v65, v65
	v_fma_f32 v50, v50, v69, v67
	v_fma_f32 v51, v51, v69, v67
	v_fma_f32 v52, v52, v69, v67
	v_fma_f32 v53, v53, v69, v67
	v_exp_f32_e32 v50, v50
	v_exp_f32_e32 v51, v51
	v_exp_f32_e32 v52, v52
	v_exp_f32_e32 v53, v53
	v_fma_f32 v42, v42, v69, v67
	v_fma_f32 v43, v43, v69, v67
	v_fma_f32 v44, v44, v69, v67
	v_fma_f32 v45, v45, v69, v67
	v_exp_f32_e32 v42, v42
	v_exp_f32_e32 v43, v43
	v_exp_f32_e32 v44, v44
	v_exp_f32_e32 v45, v45
	v_fma_f32 v38, v38, v69, v67
	v_fma_f32 v39, v39, v69, v67
	v_fma_f32 v40, v40, v69, v67
	v_fma_f32 v41, v41, v69, v67
	v_exp_f32_e32 v38, v38
	v_exp_f32_e32 v39, v39
	v_exp_f32_e32 v40, v40
; #define LAS __attribute__((address_space(3)))
; __device__ __forceinline__ unsigned cvt_pk_bf16(float lo, float hi) { const f32x2 v = {lo, hi}; const bf16x2_t r = __builtin_convertvector(v, bf16x2_t); return __builtin_bit_cast(unsigned, r); }
; __device__ __forceinline__ f32x4 mfma16(bf16x8 a, bf16x8 b, f32x4 c) { return __builtin_amdgcn_mfma_f32_16x16x32_bf16(a, b, c, 0, 0, 0); }
; __device__ __forceinline__ void xa_pair(LAS unsigned char* lds, const bf16_t* Ux, const bf16_t* Kb, const bf16_t* Vt, bf16_t* Yx, int pair, int tid) {
;     ...
;         for (int nt = 0; nt < 16; ++nt)
; #pragma unroll
;             for (int j = 0; j < 4; ++j) { const float pz = exp2f((s[nt][j] - mx) * sc); s[nt][j] = pz; l += pz; }
;         l += __shfl_xor(l, 16); l += __shfl_xor(l, 32);
;         f32x4 o[8];
; #pragma unroll
;         for (int dt = 0; dt < 8; ++dt) o[dt] = (f32x4){0.f, 0.f, 0.f, 0.f};
; #pragma unroll
;         for (int c = 0; c < 8; ++c) { union { u32x4 u; bf16x8 v; } pf;
;             pf.u.x = cvt_pk_bf16(s[2 * c][0], s[2 * c][1]); pf.u.y = cvt_pk_bf16(s[2 * c][2], s[2 * c][3]); pf.u.z = cvt_pk_bf16(s[2 * c + 1][0], s[2 * c + 1][1]); pf.u.w = cvt_pk_bf16(s[2 * c + 1][2], s[2 * c + 1][3]);
; #pragma unroll
;             for (int dt = 0; dt < 8; ++dt) { LAS const unsigned char* vr = lds + XV_OFF + (16 * dt + fr) * XV_STRIDE + (32 * c + 4 * fq) * 2; union { u32x4 u; bf16x8 v; } vf;
;                 const u32x2 lo = *(LAS const u32x2*)vr, hi = *(LAS const u32x2*)(vr + 32); vf.u.x = lo.x; vf.u.y = lo.y; vf.u.z = hi.x; vf.u.w = hi.y;
;                 o[dt] = mfma16(vf.v, pf.v, o[dt]); }
;             asm volatile("" ::: "memory"); }
	v_exp_f32_e32 v41, v41
	v_fma_f32 v34, v34, v69, v67
	v_fma_f32 v35, v35, v69, v67
	v_fma_f32 v36, v36, v69, v67
	v_fma_f32 v37, v37, v69, v67
	v_exp_f32_e32 v34, v34
	v_exp_f32_e32 v35, v35
	v_exp_f32_e32 v36, v36
	v_exp_f32_e32 v37, v37
	v_fma_f32 v30, v30, v69, v67
	v_fma_f32 v31, v31, v69, v67
	v_fma_f32 v32, v32, v69, v67
	v_fma_f32 v33, v33, v69, v67
	v_exp_f32_e32 v30, v30
	v_exp_f32_e32 v31, v31
	v_exp_f32_e32 v32, v32
	v_exp_f32_e32 v33, v33
	v_fma_f32 v26, v26, v69, v67
	v_fma_f32 v27, v27, v69, v67
	v_fma_f32 v28, v28, v69, v67
	v_fma_f32 v29, v29, v69, v67
	v_exp_f32_e32 v26, v26
	v_exp_f32_e32 v27, v27
	v_exp_f32_e32 v28, v28
	v_exp_f32_e32 v29, v29
	v_fma_f32 v22, v22, v69, v67
	v_fma_f32 v23, v23, v69, v67
	v_fma_f32 v24, v24, v69, v67
	v_fma_f32 v25, v25, v69, v67
	v_exp_f32_e32 v22, v22
	v_exp_f32_e32 v23, v23
	v_exp_f32_e32 v24, v24
	v_exp_f32_e32 v25, v25
	v_fma_f32 v18, v18, v69, v67
	v_fma_f32 v19, v19, v69, v67
	v_fma_f32 v20, v20, v69, v67
	v_fma_f32 v21, v21, v69, v67
	v_exp_f32_e32 v18, v18
	v_exp_f32_e32 v19, v19
	v_exp_f32_e32 v20, v20
	v_exp_f32_e32 v21, v21
	v_fma_f32 v10, v10, v69, v67
	v_fma_f32 v11, v11, v69, v67
	v_fma_f32 v12, v12, v69, v67
	v_fma_f32 v13, v13, v69, v67
	v_exp_f32_e32 v10, v10
	v_exp_f32_e32 v11, v11
	v_exp_f32_e32 v12, v12
	v_exp_f32_e32 v13, v13
	v_fma_f32 v2, v2, v69, v67
	v_fma_f32 v3, v3, v69, v67
	v_fma_f32 v4, v4, v69, v67
	v_fma_f32 v5, v5, v69, v67
	v_exp_f32_e32 v2, v2
	v_exp_f32_e32 v3, v3
	v_exp_f32_e32 v4, v4
	v_exp_f32_e32 v5, v5
	v_fma_f32 v14, v14, v69, v67
	v_fma_f32 v15, v15, v69, v67
	v_fma_f32 v16, v16, v69, v67
	v_fma_f32 v17, v17, v69, v67
	v_exp_f32_e32 v14, v14
	v_exp_f32_e32 v15, v15
	v_exp_f32_e32 v16, v16
	v_exp_f32_e32 v17, v17
	v_fma_f32 v6, v6, v69, v67
	v_fma_f32 v7, v7, v69, v67
	v_fma_f32 v8, v8, v69, v67
	v_fma_f32 v9, v9, v69, v67
	v_exp_f32_e32 v6, v6
	v_exp_f32_e32 v7, v7
	v_exp_f32_e32 v8, v8
	v_exp_f32_e32 v9, v9
	v_fma_f32 v54, v54, v69, v67
	v_fma_f32 v55, v55, v69, v67
	v_fma_f32 v56, v56, v69, v67
	v_fma_f32 v57, v57, v69, v67
	v_exp_f32_e32 v54, v54
	v_exp_f32_e32 v55, v55
	v_exp_f32_e32 v56, v56
	v_exp_f32_e32 v57, v57
	s_nop 0
	v_pk_add_f32 v[70:71], v[58:59], v[46:47]
	v_pk_add_f32 v[72:73], v[60:61], v[48:49]
	v_pk_add_f32 v[70:71], v[70:71], v[62:63]
	v_pk_add_f32 v[72:73], v[72:73], v[64:65]
	v_pk_add_f32 v[70:71], v[70:71], v[50:51]
	v_pk_add_f32 v[72:73], v[72:73], v[52:53]
	v_pk_add_f32 v[70:71], v[70:71], v[42:43]
	v_pk_add_f32 v[72:73], v[72:73], v[44:45]
	v_pk_add_f32 v[70:71], v[70:71], v[38:39]
	v_pk_add_f32 v[72:73], v[72:73], v[40:41]
	v_pk_add_f32 v[70:71], v[70:71], v[34:35]
	v_pk_add_f32 v[72:73], v[72:73], v[36:37]
	v_pk_add_f32 v[70:71], v[70:71], v[30:31]
	v_pk_add_f32 v[72:73], v[72:73], v[32:33]
	v_pk_add_f32 v[70:71], v[70:71], v[26:27]
	v_pk_add_f32 v[72:73], v[72:73], v[28:29]
	v_pk_add_f32 v[70:71], v[70:71], v[22:23]
	v_pk_add_f32 v[72:73], v[72:73], v[24:25]
	v_pk_add_f32 v[70:71], v[70:71], v[18:19]
	v_pk_add_f32 v[72:73], v[72:73], v[20:21]
	v_pk_add_f32 v[70:71], v[70:71], v[10:11]
	v_pk_add_f32 v[72:73], v[72:73], v[12:13]
	v_pk_add_f32 v[70:71], v[70:71], v[2:3]
	v_pk_add_f32 v[72:73], v[72:73], v[4:5]
	v_pk_add_f32 v[70:71], v[70:71], v[14:15]
	v_pk_add_f32 v[72:73], v[72:73], v[16:17]
	v_pk_add_f32 v[70:71], v[70:71], v[6:7]
	v_pk_add_f32 v[72:73], v[72:73], v[8:9]
	v_pk_add_f32 v[70:71], v[70:71], v[54:55]
	v_pk_add_f32 v[72:73], v[72:73], v[56:57]
	v_pk_add_f32 v[70:71], v[70:71], v[72:73]
	s_nop 0
	v_add_f32_e32 v68, v70, v71
	ds_bpermute_b32 v75, v124, v68
	s_waitcnt lgkmcnt(0)
	v_add_f32_e32 v68, v68, v75
	ds_bpermute_b32 v75, v125, v68
	v_cvt_pk_bf16_f32 v58, v58, v59
	v_cvt_pk_bf16_f32 v59, v60, v61
	v_cvt_pk_bf16_f32 v60, v46, v47
	v_cvt_pk_bf16_f32 v61, v48, v49
	v_cvt_pk_bf16_f32 v62, v62, v63
	v_cvt_pk_bf16_f32 v63, v64, v65
	v_cvt_pk_bf16_f32 v64, v50, v51
	v_cvt_pk_bf16_f32 v65, v52, v53
	v_cvt_pk_bf16_f32 v42, v42, v43
	v_cvt_pk_bf16_f32 v43, v44, v45
	v_cvt_pk_bf16_f32 v44, v38, v39
	v_cvt_pk_bf16_f32 v45, v40, v41
	v_cvt_pk_bf16_f32 v34, v34, v35
	v_cvt_pk_bf16_f32 v35, v36, v37
	v_cvt_pk_bf16_f32 v36, v30, v31
	v_cvt_pk_bf16_f32 v37, v32, v33
	v_cvt_pk_bf16_f32 v26, v26, v27
	v_cvt_pk_bf16_f32 v27, v28, v29
	v_cvt_pk_bf16_f32 v28, v22, v23
	v_cvt_pk_bf16_f32 v29, v24, v25
	v_cvt_pk_bf16_f32 v18, v18, v19
	v_cvt_pk_bf16_f32 v19, v20, v21
	v_cvt_pk_bf16_f32 v20, v10, v11
	v_cvt_pk_bf16_f32 v21, v12, v13
	v_cvt_pk_bf16_f32 v2, v2, v3
	v_cvt_pk_bf16_f32 v3, v4, v5
	v_cvt_pk_bf16_f32 v4, v14, v15
	v_cvt_pk_bf16_f32 v5, v16, v17
	v_cvt_pk_bf16_f32 v6, v6, v7
	v_cvt_pk_bf16_f32 v7, v8, v9
	v_cvt_pk_bf16_f32 v8, v54, v55
	v_cvt_pk_bf16_f32 v9, v56, v57
	s_waitcnt lgkmcnt(0)
	v_add_f32_e32 v68, v68, v75
	s_waitcnt lgkmcnt(8)
	v_mfma_f32_16x16x32_bf16 v[46:49], v[164:167], v[58:61], 0
	v_mfma_f32_16x16x32_bf16 v[50:53], v[168:171], v[58:61], 0
	v_mfma_f32_16x16x32_bf16 v[38:41], v[172:175], v[58:61], 0
	v_mfma_f32_16x16x32_bf16 v[30:33], v[176:179], v[58:61], 0
	ds_read2_b64 v[164:167], v224 offset0:8 offset1:12
	ds_read2_b64 v[168:171], v225 offset0:8 offset1:12
	ds_read2_b64 v[172:175], v226 offset0:8 offset1:12
	ds_read2_b64 v[176:179], v227 offset0:8 offset1:12
	s_waitcnt lgkmcnt(8)
	v_mfma_f32_16x16x32_bf16 v[22:25], v[180:183], v[58:61], 0
	v_mfma_f32_16x16x32_bf16 v[10:13], v[184:187], v[58:61], 0
	v_mfma_f32_16x16x32_bf16 v[14:17], v[188:191], v[58:61], 0
	v_mfma_f32_16x16x32_bf16 v[54:57], v[192:195], v[58:61], 0
	ds_read2_b64 v[180:183], v220 offset0:16 offset1:20
	ds_read2_b64 v[184:187], v221 offset0:16 offset1:20
	ds_read2_b64 v[188:191], v222 offset0:16 offset1:20
	ds_read2_b64 v[192:195], v223 offset0:16 offset1:20
	s_waitcnt lgkmcnt(8)
; #define LAS __attribute__((address_space(3)))
; __device__ __forceinline__ unsigned cvt_pk_bf16(float lo, float hi) { const f32x2 v = {lo, hi}; const bf16x2_t r = __builtin_convertvector(v, bf16x2_t); return __builtin_bit_cast(unsigned, r); }
; __device__ __forceinline__ f32x4 mfma16(bf16x8 a, bf16x8 b, f32x4 c) { return __builtin_amdgcn_mfma_f32_16x16x32_bf16(a, b, c, 0, 0, 0); }
; __device__ __forceinline__ void xa_pair(LAS unsigned char* lds, const bf16_t* Ux, const bf16_t* Kb, const bf16_t* Vt, bf16_t* Yx, int pair, int tid) {
;     ...
;         for (int c = 0; c < 8; ++c) { union { u32x4 u; bf16x8 v; } pf;
;             pf.u.x = cvt_pk_bf16(s[2 * c][0], s[2 * c][1]); pf.u.y = cvt_pk_bf16(s[2 * c][2], s[2 * c][3]); pf.u.z = cvt_pk_bf16(s[2 * c + 1][0], s[2 * c + 1][1]); pf.u.w = cvt_pk_bf16(s[2 * c + 1][2], s[2 * c + 1][3]);
; #pragma unroll
;             for (int dt = 0; dt < 8; ++dt) { LAS const unsigned char* vr = lds + XV_OFF + (16 * dt + fr) * XV_STRIDE + (32 * c + 4 * fq) * 2; union { u32x4 u; bf16x8 v; } vf;
;                 const u32x2 lo = *(LAS const u32x2*)vr, hi = *(LAS const u32x2*)(vr + 32); vf.u.x = lo.x; vf.u.y = lo.y; vf.u.z = hi.x; vf.u.w = hi.y;
;                 o[dt] = mfma16(vf.v, pf.v, o[dt]); }
;             asm volatile("" ::: "memory"); }
	v_mfma_f32_16x16x32_bf16 v[46:49], v[196:199], v[62:65], v[46:49]
	v_mfma_f32_16x16x32_bf16 v[50:53], v[200:203], v[62:65], v[50:53]
	v_mfma_f32_16x16x32_bf16 v[38:41], v[204:207], v[62:65], v[38:41]
	v_mfma_f32_16x16x32_bf16 v[30:33], v[212:215], v[62:65], v[30:33]
	ds_read2_b64 v[196:199], v224 offset0:16 offset1:20
	ds_read2_b64 v[200:203], v225 offset0:16 offset1:20
	ds_read2_b64 v[204:207], v226 offset0:16 offset1:20
	ds_read2_b64 v[212:215], v227 offset0:16 offset1:20
	s_waitcnt lgkmcnt(8)
	v_mfma_f32_16x16x32_bf16 v[22:25], v[164:167], v[62:65], v[22:25]
	v_mfma_f32_16x16x32_bf16 v[10:13], v[168:171], v[62:65], v[10:13]
	v_mfma_f32_16x16x32_bf16 v[14:17], v[172:175], v[62:65], v[14:17]
	v_mfma_f32_16x16x32_bf16 v[54:57], v[176:179], v[62:65], v[54:57]
	ds_read2_b64 v[164:167], v220 offset0:24 offset1:28
	ds_read2_b64 v[168:171], v221 offset0:24 offset1:28
	ds_read2_b64 v[172:175], v222 offset0:24 offset1:28
	ds_read2_b64 v[176:179], v223 offset0:24 offset1:28
	s_waitcnt lgkmcnt(8)
	v_mfma_f32_16x16x32_bf16 v[46:49], v[180:183], v[42:45], v[46:49]
	v_mfma_f32_16x16x32_bf16 v[50:53], v[184:187], v[42:45], v[50:53]
	v_mfma_f32_16x16x32_bf16 v[38:41], v[188:191], v[42:45], v[38:41]
	v_mfma_f32_16x16x32_bf16 v[30:33], v[192:195], v[42:45], v[30:33]
	ds_read2_b64 v[180:183], v224 offset0:24 offset1:28
	ds_read2_b64 v[184:187], v225 offset0:24 offset1:28
	ds_read2_b64 v[188:191], v226 offset0:24 offset1:28
	ds_read2_b64 v[192:195], v227 offset0:24 offset1:28
	s_waitcnt lgkmcnt(8)
	v_mfma_f32_16x16x32_bf16 v[22:25], v[196:199], v[42:45], v[22:25]
	v_mfma_f32_16x16x32_bf16 v[10:13], v[200:203], v[42:45], v[10:13]
	v_mfma_f32_16x16x32_bf16 v[14:17], v[204:207], v[42:45], v[14:17]
	v_mfma_f32_16x16x32_bf16 v[54:57], v[212:215], v[42:45], v[54:57]
	ds_read2_b64 v[196:199], v220 offset0:32 offset1:36
	ds_read2_b64 v[200:203], v221 offset0:32 offset1:36
	ds_read2_b64 v[204:207], v222 offset0:32 offset1:36
	ds_read2_b64 v[212:215], v223 offset0:32 offset1:36
	s_waitcnt lgkmcnt(8)
	v_mfma_f32_16x16x32_bf16 v[46:49], v[164:167], v[34:37], v[46:49]
	v_mfma_f32_16x16x32_bf16 v[50:53], v[168:171], v[34:37], v[50:53]
	v_mfma_f32_16x16x32_bf16 v[38:41], v[172:175], v[34:37], v[38:41]
	v_mfma_f32_16x16x32_bf16 v[30:33], v[176:179], v[34:37], v[30:33]
	ds_read2_b64 v[164:167], v224 offset0:32 offset1:36
	ds_read2_b64 v[168:171], v225 offset0:32 offset1:36
	ds_read2_b64 v[172:175], v226 offset0:32 offset1:36
	ds_read2_b64 v[176:179], v227 offset0:32 offset1:36
	s_waitcnt lgkmcnt(8)
	v_mfma_f32_16x16x32_bf16 v[22:25], v[180:183], v[34:37], v[22:25]
	v_mfma_f32_16x16x32_bf16 v[10:13], v[184:187], v[34:37], v[10:13]
	v_mfma_f32_16x16x32_bf16 v[14:17], v[188:191], v[34:37], v[14:17]
	v_mfma_f32_16x16x32_bf16 v[54:57], v[192:195], v[34:37], v[54:57]
	ds_read2_b64 v[180:183], v220 offset0:40 offset1:44
	ds_read2_b64 v[184:187], v221 offset0:40 offset1:44
	ds_read2_b64 v[188:191], v222 offset0:40 offset1:44
	ds_read2_b64 v[192:195], v223 offset0:40 offset1:44
	s_waitcnt lgkmcnt(8)
	v_mfma_f32_16x16x32_bf16 v[46:49], v[196:199], v[26:29], v[46:49]
	v_mfma_f32_16x16x32_bf16 v[50:53], v[200:203], v[26:29], v[50:53]
	v_mfma_f32_16x16x32_bf16 v[38:41], v[204:207], v[26:29], v[38:41]
	v_mfma_f32_16x16x32_bf16 v[30:33], v[212:215], v[26:29], v[30:33]
	ds_read2_b64 v[196:199], v224 offset0:40 offset1:44
	ds_read2_b64 v[200:203], v225 offset0:40 offset1:44
	ds_read2_b64 v[204:207], v226 offset0:40 offset1:44
	ds_read2_b64 v[212:215], v227 offset0:40 offset1:44
	s_waitcnt lgkmcnt(8)
	v_mfma_f32_16x16x32_bf16 v[22:25], v[164:167], v[26:29], v[22:25]
	v_mfma_f32_16x16x32_bf16 v[10:13], v[168:171], v[26:29], v[10:13]
	v_mfma_f32_16x16x32_bf16 v[14:17], v[172:175], v[26:29], v[14:17]
	v_mfma_f32_16x16x32_bf16 v[54:57], v[176:179], v[26:29], v[54:57]
	ds_read2_b64 v[164:167], v220 offset0:48 offset1:52
	ds_read2_b64 v[168:171], v221 offset0:48 offset1:52
	ds_read2_b64 v[172:175], v222 offset0:48 offset1:52
	ds_read2_b64 v[176:179], v223 offset0:48 offset1:52
	s_waitcnt lgkmcnt(8)
	v_mfma_f32_16x16x32_bf16 v[46:49], v[180:183], v[18:21], v[46:49]
	v_mfma_f32_16x16x32_bf16 v[50:53], v[184:187], v[18:21], v[50:53]
	v_mfma_f32_16x16x32_bf16 v[38:41], v[188:191], v[18:21], v[38:41]
	v_mfma_f32_16x16x32_bf16 v[30:33], v[192:195], v[18:21], v[30:33]
	ds_read2_b64 v[180:183], v224 offset0:48 offset1:52
	ds_read2_b64 v[184:187], v225 offset0:48 offset1:52
	ds_read2_b64 v[188:191], v226 offset0:48 offset1:52
	ds_read2_b64 v[192:195], v227 offset0:48 offset1:52
	s_waitcnt lgkmcnt(8)
	v_mfma_f32_16x16x32_bf16 v[22:25], v[196:199], v[18:21], v[22:25]
	v_mfma_f32_16x16x32_bf16 v[10:13], v[200:203], v[18:21], v[10:13]
	v_mfma_f32_16x16x32_bf16 v[14:17], v[204:207], v[18:21], v[14:17]
	v_mfma_f32_16x16x32_bf16 v[54:57], v[212:215], v[18:21], v[54:57]
	ds_read2_b64 v[196:199], v220 offset0:56 offset1:60
	ds_read2_b64 v[200:203], v221 offset0:56 offset1:60
	ds_read2_b64 v[204:207], v222 offset0:56 offset1:60
	ds_read2_b64 v[212:215], v223 offset0:56 offset1:60
	s_waitcnt lgkmcnt(8)
	v_mfma_f32_16x16x32_bf16 v[46:49], v[164:167], v[2:5], v[46:49]
	v_mfma_f32_16x16x32_bf16 v[50:53], v[168:171], v[2:5], v[50:53]
	v_mfma_f32_16x16x32_bf16 v[38:41], v[172:175], v[2:5], v[38:41]
	v_mfma_f32_16x16x32_bf16 v[30:33], v[176:179], v[2:5], v[30:33]
	ds_read2_b64 v[164:167], v224 offset0:56 offset1:60
	ds_read2_b64 v[168:171], v225 offset0:56 offset1:60
	ds_read2_b64 v[172:175], v226 offset0:56 offset1:60
	ds_read2_b64 v[176:179], v227 offset0:56 offset1:60
	s_waitcnt lgkmcnt(8)
; #define LAS __attribute__((address_space(3)))
; __device__ __forceinline__ void st_bf4(bf16_t* p, f32x4 v) { u32x2 w; w.x = cvt_pk_bf16(v[0], v[1]); w.y = cvt_pk_bf16(v[2], v[3]); *(u32x2*)p = w; }
; __device__ __forceinline__ f32x4 mfma16(bf16x8 a, bf16x8 b, f32x4 c) { return __builtin_amdgcn_mfma_f32_16x16x32_bf16(a, b, c, 0, 0, 0); }
; #define PH_BEGIN const int zi = opaque0(); unsigned char* ws = P.ws + zi; float* const OUT = P.out + zi; (void)OUT; const int tid = opqv((int)threadIdx.x); const int bid = opqs((int)blockIdx.x); const int G = opqs((int)gridDim.x); (void)tid; (void)bid; (void)G; unsigned char* WB = ws + WS_WB; float* SS = (float*)(ws + WS_SS); (void)WB; (void)SS; (void)zi;
; __device__ __forceinline__ void xa_pair(LAS unsigned char* lds, const bf16_t* Ux, const bf16_t* Kb, const bf16_t* Vt, bf16_t* Yx, int pair, int tid) {
;     ...
;             for (int dt = 0; dt < 8; ++dt) { LAS const unsigned char* vr = lds + XV_OFF + (16 * dt + fr) * XV_STRIDE + (32 * c + 4 * fq) * 2; union { u32x4 u; bf16x8 v; } vf;
;                 const u32x2 lo = *(LAS const u32x2*)vr, hi = *(LAS const u32x2*)(vr + 32); vf.u.x = lo.x; vf.u.y = lo.y; vf.u.z = hi.x; vf.u.w = hi.y;
;                 o[dt] = mfma16(vf.v, pf.v, o[dt]); }
;             asm volatile("" ::: "memory"); }
;         const float il = 1.0f / l;
; #pragma unroll
;         for (int dt = 0; dt < 8; ++dt) st_bf4(Yx + (size_t)t * 512 + h * 128 + 16 * dt + 4 * fq, o[dt] * il);
; __global__ void __launch_bounds__(512) mega(Params P) {
;     ...
;             { PH_BEGIN convT_w<0>(INP(4) + (size_t)l * FF * D, D, 0, nullptr, (bf16_t*)(WB + WB_W1B), FF, FF, D, bid * 8 + (tid >> 6), G * 8, tid & 63, 1408); }
;             { PH_BEGIN convT_w<2>(INP(7) + (size_t)l * D * 6928, 6928, 0, INP(5) + (size_t)l * D, (bf16_t*)(WB + WB_WIN), D, D, 4096, bid * 8 + (tid >> 6), G * 8, tid & 63, 2112); }
	v_mfma_f32_16x16x32_bf16 v[22:25], v[180:183], v[2:5], v[22:25]
	v_mfma_f32_16x16x32_bf16 v[10:13], v[184:187], v[2:5], v[10:13]
	v_mfma_f32_16x16x32_bf16 v[14:17], v[188:191], v[2:5], v[14:17]
	v_mfma_f32_16x16x32_bf16 v[54:57], v[192:195], v[2:5], v[54:57]
	s_waitcnt lgkmcnt(4)
	v_mfma_f32_16x16x32_bf16 v[46:49], v[196:199], v[6:9], v[46:49]
	v_mfma_f32_16x16x32_bf16 v[50:53], v[200:203], v[6:9], v[50:53]
	v_mfma_f32_16x16x32_bf16 v[38:41], v[204:207], v[6:9], v[38:41]
	v_mfma_f32_16x16x32_bf16 v[30:33], v[212:215], v[6:9], v[30:33]
	s_waitcnt lgkmcnt(0)
	v_mfma_f32_16x16x32_bf16 v[22:25], v[164:167], v[6:9], v[22:25]
	v_mfma_f32_16x16x32_bf16 v[10:13], v[168:171], v[6:9], v[10:13]
	v_mfma_f32_16x16x32_bf16 v[14:17], v[172:175], v[6:9], v[14:17]
	v_mfma_f32_16x16x32_bf16 v[54:57], v[176:179], v[6:9], v[54:57]
	v_div_scale_f32 v75, s[8:9], v68, v68, 1.0
	v_rcp_f32_e32 v76, v75
	s_movk_i32 s8, 0x80
	v_fma_f32 v77, -v75, v76, 1.0
	v_fmac_f32_e32 v76, v77, v76
	v_div_scale_f32 v77, vcc, 1.0, v68, 1.0
	v_mul_f32_e32 v70, v77, v76
	v_fma_f32 v71, -v75, v70, v77
	v_fmac_f32_e32 v70, v71, v76
	v_fma_f32 v75, -v75, v70, v77
	v_div_fmas_f32 v75, v75, v76, v70
	v_div_fixup_f32 v74, v75, v68, 1.0
	v_lshl_add_u64 v[72:73], v[112:113], 0, v[114:115]
	v_pk_mul_f32 v[46:47], v[74:75], v[46:47] op_sel_hi:[0,1]
	v_pk_mul_f32 v[48:49], v[74:75], v[48:49] op_sel_hi:[0,1]
	v_cvt_pk_bf16_f32 v46, v46, v47
	v_cvt_pk_bf16_f32 v47, v48, v49
	global_store_dwordx2 v[72:73], v[46:47], off
	v_pk_mul_f32 v[50:51], v[74:75], v[50:51] op_sel_hi:[0,1]
	v_pk_mul_f32 v[52:53], v[74:75], v[52:53] op_sel_hi:[0,1]
	v_cvt_pk_bf16_f32 v50, v50, v51
	v_cvt_pk_bf16_f32 v51, v52, v53
	global_store_dwordx2 v[72:73], v[50:51], off offset:32
	v_pk_mul_f32 v[38:39], v[74:75], v[38:39] op_sel_hi:[0,1]
	v_pk_mul_f32 v[40:41], v[74:75], v[40:41] op_sel_hi:[0,1]
	v_cvt_pk_bf16_f32 v38, v38, v39
	v_cvt_pk_bf16_f32 v39, v40, v41
	global_store_dwordx2 v[72:73], v[38:39], off offset:64
	v_pk_mul_f32 v[30:31], v[74:75], v[30:31] op_sel_hi:[0,1]
	v_pk_mul_f32 v[32:33], v[74:75], v[32:33] op_sel_hi:[0,1]
	v_cvt_pk_bf16_f32 v30, v30, v31
	v_cvt_pk_bf16_f32 v31, v32, v33
	global_store_dwordx2 v[72:73], v[30:31], off offset:96
	v_pk_mul_f32 v[22:23], v[74:75], v[22:23] op_sel_hi:[0,1]
	v_pk_mul_f32 v[24:25], v[74:75], v[24:25] op_sel_hi:[0,1]
	v_cvt_pk_bf16_f32 v22, v22, v23
	v_cvt_pk_bf16_f32 v23, v24, v25
	global_store_dwordx2 v[72:73], v[22:23], off offset:128
	v_pk_mul_f32 v[10:11], v[74:75], v[10:11] op_sel_hi:[0,1]
	v_pk_mul_f32 v[12:13], v[74:75], v[12:13] op_sel_hi:[0,1]
	v_cvt_pk_bf16_f32 v10, v10, v11
	v_cvt_pk_bf16_f32 v11, v12, v13
	global_store_dwordx2 v[72:73], v[10:11], off offset:160
	v_pk_mul_f32 v[14:15], v[74:75], v[14:15] op_sel_hi:[0,1]
	v_pk_mul_f32 v[16:17], v[74:75], v[16:17] op_sel_hi:[0,1]
	v_cvt_pk_bf16_f32 v14, v14, v15
	v_cvt_pk_bf16_f32 v15, v16, v17
	global_store_dwordx2 v[72:73], v[14:15], off offset:192
	v_pk_mul_f32 v[54:55], v[74:75], v[54:55] op_sel_hi:[0,1]
	v_pk_mul_f32 v[56:57], v[74:75], v[56:57] op_sel_hi:[0,1]
	v_cvt_pk_bf16_f32 v54, v54, v55
	v_cvt_pk_bf16_f32 v55, v56, v57
	global_store_dwordx2 v[72:73], v[54:55], off offset:224
	s_and_b64 vcc, exec, s[6:7]
	s_mov_b64 s[6:7], 0
	s_cbranch_vccnz .LBB0_318
	s_mov_b32 s11, 1
	s_and_b64 vcc, exec, s[4:5]
	s_barrier
	s_cbranch_vccz .LBB0_317
	s_mul_i32 s1, s0, 0xab
	s_bfe_u32 s1, s1, 0x5000b
	s_cmp_eq_u32 s1, 3
	s_cbranch_scc1 .Lp5_noextra
	s_add_i32 s1, s1, 1
	s_mov_b32 s100, 4
	s_movk_i32 s101, 0x80
	s_and_b32 s16, s1, 0xffff
	s_lshl_b32 s19, s16, 10
	s_mov_b32 s28, 0xc000
	s_mov_b32 s29, 0xe000
	s_mov_b32 s72, 0xd000
	s_mov_b32 s73, 0x9000
	s_movk_i32 s74, 0x7000
	s_sub_i32 s2, s2, 0x80
	s_movk_i32 s3, 0x80
	s_branch .Lp0_mov_entry
.Lp5_back:
	s_mov_b32 s100, 0
	s_mul_i32 s1, s0, 0xab
	s_bfe_u32 s1, s1, 0x5000b
	s_and_b32 s2, s2, 0xffff
	s_add_i32 s2, s2, 0x80
	s_movk_i32 s3, 0x100
.Lp5_noextra:
	s_mov_b64 s[4:5], 0
.LBB0_321:
	s_and_b64 vcc, exec, s[4:5]
	s_cbranch_vccz .LBB0_370
	s_mov_b32 s14, s63
	s_ashr_i32 s15, s14, 31
	v_mov_b32_e32 v32, v232
	s_mov_b32 s20, s2
	s_mov_b32 s4, s3
	s_add_u32 s6, s92, s14
	s_addc_u32 s7, s93, s15
	s_lshl_b32 s4, s20, 2
	s_and_b32 s4, s4, 28
	s_ashr_i32 s18, s20, 5
	s_add_i32 s4, s4, s18
	v_ashrrev_i32_e32 v36, 8, v32
	v_lshlrev_b32_e32 v2, 5, v36
	s_ashr_i32 s5, s4, 31
	v_lshlrev_b32_e32 v8, 4, v32
	s_lshl_b64 s[4:5], s[4:5], 12
	s_waitcnt lgkmcnt(0)
	v_ashrrev_i32_e32 v3, 31, v2
	v_and_b32_e32 v0, 0xf0, v8
	v_lshl_add_u64 v[30:31], s[4:5], 0, v[2:3]
	v_lshl_add_u64 v[2:3], s[6:7], 0, v[0:1]
	s_mov_b64 s[4:5], 0xe100000
	v_lshl_add_u64 v[2:3], v[2:3], 0, s[4:5]
	s_movk_i32 s4, 0x100
	v_or_b32_sdwa v9, v32, s4 dst_sel:DWORD dst_unused:UNUSED_PAD src0_sel:BYTE_0 src1_sel:DWORD
	v_bfe_u32 v37, v32, 4, 4
	v_lshrrev_b32_e32 v38, 4, v9
	v_or_b32_e32 v4, v30, v37
	v_mov_b32_e32 v5, v31
	v_or_b32_e32 v6, v30, v38
	v_mov_b32_e32 v7, v31
	v_lshlrev_b64 v[4:5], 8, v[4:5]
	v_lshlrev_b64 v[6:7], 8, v[6:7]
	v_lshl_add_u64 v[4:5], v[2:3], 0, v[4:5]
	v_lshl_add_u64 v[2:3], v[2:3], 0, v[6:7]
	v_and_b32_e32 v0, 0x180, v8
	global_load_dwordx4 v[26:29], v[4:5], off
	global_load_dwordx4 v[22:25], v[2:3], off
	v_lshl_add_u64 v[2:3], s[6:7], 0, v[0:1]
	v_and_b32_e32 v0, 0x70, v8
	v_bfe_u32 v35, v32, 5, 3
	v_lshl_add_u64 v[2:3], v[2:3], 0, v[0:1]
	s_mov_b64 s[4:5], 0x12100000
	v_or_b32_e32 v4, v30, v35
	v_mov_b32_e32 v5, v31
	v_lshrrev_b32_e32 v34, 5, v9
	v_lshl_add_u64 v[2:3], v[2:3], 0, s[4:5]
	v_lshlrev_b64 v[6:7], 9, v[4:5]
	v_or_b32_e32 v8, v30, v34
	v_mov_b32_e32 v9, v31
	v_lshl_add_u64 v[6:7], v[2:3], 0, v[6:7]
	v_lshlrev_b64 v[8:9], 9, v[8:9]
	v_lshl_add_u64 v[8:9], v[2:3], 0, v[8:9]
	global_load_dwordx4 v[18:21], v[6:7], off
	global_load_dwordx4 v[14:17], v[8:9], off
	v_or_b32_e32 v6, 16, v4
	v_mov_b32_e32 v7, v31
	v_or_b32_e32 v4, 24, v4
	v_lshlrev_b64 v[6:7], 9, v[6:7]
	v_lshlrev_b64 v[4:5], 9, v[4:5]
	v_lshl_add_u64 v[6:7], v[2:3], 0, v[6:7]
	v_lshl_add_u64 v[2:3], v[2:3], 0, v[4:5]
	global_load_dwordx4 v[10:13], v[6:7], off
	s_nop 0
	global_load_dwordx4 v[2:5], v[2:3], off
	s_movk_i32 s4, 0x80
	v_readfirstlane_b32 s10, v32
	v_cmp_lt_u32_sdwa s[4:5], v32, s4 src0_sel:BYTE_0 src1_sel:DWORD
	v_mov_b32_e32 v6, 0
	v_lshrrev_b32_sdwa v33, v235, v32 dst_sel:DWORD dst_unused:UNUSED_PAD src0_sel:DWORD src1_sel:BYTE_0
	v_mov_b32_e32 v7, 0
	v_mov_b32_e32 v8, 0
	v_mov_b32_e32 v9, 0
	s_and_saveexec_b64 s[8:9], s[4:5]
	s_cbranch_execz .LBB0_324
	v_or_b32_e32 v30, v30, v33
	v_lshlrev_b64 v[6:7], 8, v[30:31]
	v_lshlrev_b32_sdwa v0, v235, v32 dst_sel:DWORD dst_unused:UNUSED_PAD src0_sel:DWORD src1_sel:BYTE_0
	v_lshl_add_u64 v[6:7], s[6:7], 0, v[6:7]
	s_lshl_b32 s6, s20, 3
	s_and_b32 s62, s6, 0xc0
	v_and_b32_e32 v0, 12, v0
	v_lshl_add_u64 v[6:7], v[6:7], 0, s[62:63]
	v_lshlrev_b32_e32 v0, 2, v0
	v_lshl_add_u64 v[6:7], v[6:7], 0, v[0:1]
	v_add_co_u32_e32 v6, vcc, 0x10100000, v6
	s_nop 1
	v_addc_co_u32_e32 v7, vcc, 0, v7, vcc
	global_load_dwordx4 v[6:9], v[6:7], off

; #define PH_BEGIN const int zi = opaque0(); unsigned char* ws = P.ws + zi; float* const OUT = P.out + zi; (void)OUT; const int tid = opqv((int)threadIdx.x); const int bid = opqs((int)blockIdx.x); const int G = opqs((int)gridDim.x); (void)tid; (void)bid; (void)G; unsigned char* WB = ws + WS_WB; float* SS = (float*)(ws + WS_SS); (void)WB; (void)SS; (void)zi;
; __global__ void __launch_bounds__(512) mega(Params P) {
;     ...
;             { PH_BEGIN convT_w<1>(INP(3) + (size_t)l * D * 2 * FF, 2 * FF, 0, INP(2) + (size_t)l * D, (bf16_t*)(WB + WB_W1A), D, D, 2 * FF, bid * 8 + (tid >> 6), G * 8, tid & 63, 0); }
;             { PH_BEGIN convT_w<0>(INP(4) + (size_t)l * FF * D, D, 0, nullptr, (bf16_t*)(WB + WB_W1B), FF, FF, D, bid * 8 + (tid >> 6), G * 8, tid & 63, 1408); }
;             { PH_BEGIN convT_w<2>(INP(7) + (size_t)l * D * 6928, 6928, 0, INP(5) + (size_t)l * D, (bf16_t*)(WB + WB_WIN), D, D, 4096, bid * 8 + (tid >> 6), G * 8, tid & 63, 2112); }
;             { PH_BEGIN convT_w<0>(INP(7) + (size_t)l * D * 6928, 6928, 3856, INP(5) + (size_t)l * D, (bf16_t*)(WB + WB_WG), D, D, 3072, bid * 8 + (tid >> 6), G * 8, tid & 63, 3136); }
;             for (int j = 0; j < 3; ++j) { PH_BEGIN convT_w<0>(INP(27) + ((size_t)l * 3 + j) * 512 * D, D, 0, nullptr, (bf16_t*)(WB + WB_WBR) + (size_t)j * D * 512, 512, 512, D, bid * 8 + (tid >> 6), G * 8, tid & 63, 3904 + 128 * j); }
;             { PH_BEGIN convT_w<0>(INP(28) + (size_t)l * D * D, D, 0, nullptr, (bf16_t*)(WB + WB_WO), D, D, D, bid * 8 + (tid >> 6), G * 8, tid & 63, 4288); }
;             { PH_BEGIN convT_w<0>(INP(26) + (size_t)l * D * D, D, 0, INP(6) + (size_t)l * D, (bf16_t*)(WB + WB_WKV), D, D, D, bid * 8 + (tid >> 6), G * 8, tid & 63, 4544); }
;             { PH_BEGIN convT_w<1>(INP(30) + (size_t)l * D * 2 * FF, 2 * FF, 0, INP(29) + (size_t)l * D, (bf16_t*)(WB + WB_W2A), D, D, 2 * FF, bid * 8 + (tid >> 6), G * 8, tid & 63, 4800); }
;             { PH_BEGIN convT_w<0>(INP(31) + (size_t)l * FF * D, D, 0, nullptr, (bf16_t*)(WB + WB_W2B), FF, FF, D, bid * 8 + (tid >> 6), G * 8, tid & 63, 6208); }
.LBB0_681:
	s_cmpk_lt_u32 s2, 0x80
	s_cbranch_scc1 .Lp1_noextra
	s_cmpk_gt_u32 s2, 0xef
	s_cbranch_scc1 .Lp1_noextra
	s_mul_i32 s1, s0, 0xab
	s_bfe_u32 s1, s1, 0x5000b
	s_and_b32 s16, s1, 0xffff
	s_lshl_b32 s19, s16, 10
	s_mov_b32 s28, 0xc000
	s_mov_b32 s29, 0xe000
	s_mov_b32 s72, 0xd000
	s_mov_b32 s73, 0x9000
	s_movk_i32 s74, 0x7000
	s_sub_i32 s2, s2, 0x80
	s_mov_b32 s100, 1
	s_movk_i32 s101, 0x70
	s_mul_i32 s17, s16, 0x580000
	s_or_b32 s2, s2, 0x10000
	s_mov_b32 s3, 0x100000
	s_branch .Lp0_mov_entry

; #define PH_BEGIN const int zi = opaque0(); unsigned char* ws = P.ws + zi; float* const OUT = P.out + zi; (void)OUT; const int tid = opqv((int)threadIdx.x); const int bid = opqs((int)blockIdx.x); const int G = opqs((int)gridDim.x); (void)tid; (void)bid; (void)G; unsigned char* WB = ws + WS_WB; float* SS = (float*)(ws + WS_SS); (void)WB; (void)SS; (void)zi;
; template <int MAP>
; __device__ __forceinline__ void convT_w(const float* src, int ld, int coff, const float* g, bf16_t* dst, int K, int Kd, int Nd, int wslot, int nslots, int lane, int tile_base) {
;     const int nkt = K >> 4, nnt = (Nd + 255) >> 8, ntile = nkt * nnt;
;     for (int t = ((wslot - tile_base) % nslots + nslots) % nslots; t < ntile; t += nslots) {
;         const int kt = t % nkt, ntl = t / nkt, k0 = kt * 16, n = ntl * 256 + lane * 4; const int c = (n < Nd) ? colmap<MAP>(n) : -1;
;         const float* sp = src + (size_t)k0 * ld + coff + (c >= 0 ? c : 0);
;         f32x4 v[16], gv[4];
; __global__ void __launch_bounds__(512) mega(Params P) {
;     ...
;             { PH_BEGIN convT_w<0>(INP(4) + (size_t)l * FF * D, D, 0, nullptr, (bf16_t*)(WB + WB_W1B), FF, FF, D, bid * 8 + (tid >> 6), G * 8, tid & 63, 1408); }
.LBB0_690:
	s_or_b64 exec, exec, s[6:7]
	s_cmp_eq_u32 s100, 3
	s_cbranch_scc0 .Lh690_done
	s_or_b32 s2, s2, 0x10000
	s_mov_b32 s3, 0x100000
.Lh690_done:
.Lp0_mov_entry:
	s_mov_b32 s6, s63
	v_mov_b32_e32 v0, v232
	s_mov_b32 s4, s2
	s_mov_b32 s5, s3
	s_lshl_b32 s14, s5, 3
	s_abs_i32 s5, s14
	v_cvt_f32_u32_e32 v2, s5
	v_ashrrev_i32_e32 v3, 6, v0
	v_lshl_add_u32 v3, s4, 3, v3
	v_add_u32_e32 v3, 0xfffffa80, v3
	v_rcp_iflag_f32_e32 v2, v2
	v_sub_u32_e32 v5, 0, v3
	s_sub_i32 s4, 0, s5
	v_ashrrev_i32_e32 v4, 31, v3
	v_mul_f32_e32 v2, 0x4f7ffffe, v2
	v_cvt_u32_f32_e32 v2, v2
	v_max_i32_e32 v3, v3, v5
	s_mul_i32 s18, s16, 0x2c0000
	v_mul_lo_u32 v5, s4, v2
	v_mul_hi_u32 v5, v2, v5
	v_add_u32_e32 v2, v2, v5
	v_mul_hi_u32 v5, v3, v2
	v_mul_lo_u32 v5, v5, s5
	v_sub_u32_e32 v3, v3, v5
	v_subrev_u32_e32 v5, s5, v3
	v_cmp_le_u32_e32 vcc, s5, v3
	s_movk_i32 s4, 0x2c0
	s_nop 0
	v_cndmask_b32_e32 v3, v3, v5, vcc
	v_subrev_u32_e32 v5, s5, v3
	v_cmp_le_u32_e32 vcc, s5, v3
	s_nop 1
	v_cndmask_b32_e32 v3, v3, v5, vcc
	v_xor_b32_e32 v3, v3, v4
	v_sub_u32_e32 v3, v3, v4
	v_add_u32_e32 v3, s14, v3
	v_sub_u32_e32 v5, 0, v3
	v_ashrrev_i32_e32 v4, 31, v3
	v_max_i32_e32 v3, v3, v5
	v_mul_hi_u32 v2, v3, v2
	v_mul_lo_u32 v2, v2, s5
	v_sub_u32_e32 v2, v3, v2
	v_subrev_u32_e32 v3, s5, v2
	v_cmp_le_u32_e32 vcc, s5, v2
	s_nop 1
	v_cndmask_b32_e32 v2, v2, v3, vcc
	v_subrev_u32_e32 v3, s5, v2
	v_cmp_le_u32_e32 vcc, s5, v2
	s_nop 1
	v_cndmask_b32_e32 v2, v2, v3, vcc
	v_xor_b32_e32 v2, v2, v4
	v_sub_u32_e32 v3, v2, v4
	v_cmp_gt_i32_e32 vcc, s4, v3
	s_and_saveexec_b64 s[4:5], vcc
	s_cbranch_execz .LBB0_695
	v_readlane_b32 s44, v253, 21
	s_lshl_b32 s7, s18, 2
	v_readlane_b32 s52, v253, 29
	v_readlane_b32 s53, v253, 30
	s_add_u32 s8, s52, s7
	s_addc_u32 s9, s53, 0
	s_ashr_i32 s7, s6, 31
	s_add_u32 s10, s92, s6
	s_addc_u32 s11, s93, s7
	s_lshl_b64 s[6:7], s[6:7], 2
	s_add_u32 s6, s8, s6
	s_addc_u32 s7, s9, s7
	s_add_u32 s8, s10, 0xf00000
	v_lshlrev_b32_e32 v0, 2, v0
	s_addc_u32 s9, s11, 0
	v_and_b32_e32 v4, 0xfc, v0
	v_lshlrev_b32_e32 v2, 4, v3
	s_lshl_b32 s15, s14, 4
	s_mov_b64 s[10:11], 0
	v_readlane_b32 s45, v253, 22
	v_readlane_b32 s46, v253, 23
	v_readlane_b32 s47, v253, 24
	v_readlane_b32 s48, v253, 25
	v_readlane_b32 s49, v253, 26
	v_readlane_b32 s50, v253, 27
	v_readlane_b32 s51, v253, 28
	v_readlane_b32 s54, v253, 31
	v_readlane_b32 s55, v253, 32
	v_readlane_b32 s56, v253, 33
	v_readlane_b32 s57, v253, 34
	v_readlane_b32 s58, v253, 35
	v_readlane_b32 s59, v253, 36
	s_branch .LBB0_693

; __device__ __forceinline__ unsigned cvt_pk_bf16(float lo, float hi) { const f32x2 v = {lo, hi}; const bf16x2_t r = __builtin_convertvector(v, bf16x2_t); return __builtin_bit_cast(unsigned, r); }
; #define PH_BEGIN const int zi = opaque0(); unsigned char* ws = P.ws + zi; float* const OUT = P.out + zi; (void)OUT; const int tid = opqv((int)threadIdx.x); const int bid = opqs((int)blockIdx.x); const int G = opqs((int)gridDim.x); (void)tid; (void)bid; (void)G; unsigned char* WB = ws + WS_WB; float* SS = (float*)(ws + WS_SS); (void)WB; (void)SS; (void)zi;
; template <int MAP>
; __device__ __forceinline__ void convT_w(const float* src, int ld, int coff, const float* g, bf16_t* dst, int K, int Kd, int Nd, int wslot, int nslots, int lane, int tile_base) {
;     ...
;             for (int j = 0; j < 4; ++j) { u32x4 lo, hi;
;                 lo.x = cvt_pk_bf16(v[0][j], v[1][j]); lo.y = cvt_pk_bf16(v[2][j], v[3][j]); lo.z = cvt_pk_bf16(v[4][j], v[5][j]); lo.w = cvt_pk_bf16(v[6][j], v[7][j]);
;                 hi.x = cvt_pk_bf16(v[8][j], v[9][j]); hi.y = cvt_pk_bf16(v[10][j], v[11][j]); hi.z = cvt_pk_bf16(v[12][j], v[13][j]); hi.w = cvt_pk_bf16(v[14][j], v[15][j]);
;                 bf16_t* dp = dst + (size_t)(n + j) * Kd + k0; *(u32x4*)dp = lo; *(u32x4*)(dp + 8) = hi; }
;         }
;     }
; __global__ void __launch_bounds__(512) mega(Params P) {
;     ...
;             { PH_BEGIN convT_w<2>(INP(7) + (size_t)l * D * 6928, 6928, 0, INP(5) + (size_t)l * D, (bf16_t*)(WB + WB_WIN), D, D, 4096, bid * 8 + (tid >> 6), G * 8, tid & 63, 2112); }
;             { PH_BEGIN convT_w<0>(INP(7) + (size_t)l * D * 6928, 6928, 3856, INP(5) + (size_t)l * D, (bf16_t*)(WB + WB_WG), D, D, 3072, bid * 8 + (tid >> 6), G * 8, tid & 63, 3136); }
.LBB0_701:
	s_mov_b32 s43, 0x5e000
	s_mov_b32 s42, 0x57000
	s_mov_b32 s41, 0x51000
	s_mov_b32 s40, 0x4a000
	s_mov_b32 s39, 0x43000
	s_mov_b32 s38, 0x36000
	s_mov_b32 s37, 0x2f000
	s_mov_b32 s36, 0x28000
	s_movk_i32 s31, 0x6c40
	s_mov_b32 s30, 0x3c000
	s_mov_b32 s27, 0x21000
	s_mov_b32 s26, 0x1b000
	s_mov_b32 s23, 0x14000
	s_or_b64 exec, exec, s[4:5]
	s_cmp_eq_u32 s100, 4
	s_cbranch_scc1 .Lp5_back
	s_cmp_eq_u32 s100, 1
	s_cbranch_scc1 .Lh701_off
	s_or_b32 s2, s2, 0x10000
	s_mov_b32 s3, 0x100000
	s_branch .Lh701_done

; #define PH_BEGIN const int zi = opaque0(); unsigned char* ws = P.ws + zi; float* const OUT = P.out + zi; (void)OUT; const int tid = opqv((int)threadIdx.x); const int bid = opqs((int)blockIdx.x); const int G = opqs((int)gridDim.x); (void)tid; (void)bid; (void)G; unsigned char* WB = ws + WS_WB; float* SS = (float*)(ws + WS_SS); (void)WB; (void)SS; (void)zi;
; template <int MAP>
; __device__ __forceinline__ void convT_w(const float* src, int ld, int coff, const float* g, bf16_t* dst, int K, int Kd, int Nd, int wslot, int nslots, int lane, int tile_base) {
;     const int nkt = K >> 4, nnt = (Nd + 255) >> 8, ntile = nkt * nnt;
;     for (int t = ((wslot - tile_base) % nslots + nslots) % nslots; t < ntile; t += nslots) {
;         const int kt = t % nkt, ntl = t / nkt, k0 = kt * 16, n = ntl * 256 + lane * 4; const int c = (n < Nd) ? colmap<MAP>(n) : -1;
;         const float* sp = src + (size_t)k0 * ld + coff + (c >= 0 ? c : 0);
;         f32x4 v[16], gv[4];
; __global__ void __launch_bounds__(512) mega(Params P) {
;     ...
;             { PH_BEGIN convT_w<0>(INP(7) + (size_t)l * D * 6928, 6928, 3856, INP(5) + (size_t)l * D, (bf16_t*)(WB + WB_WG), D, D, 3072, bid * 8 + (tid >> 6), G * 8, tid & 63, 3136); }
.Lh701_done:
	s_mov_b32 s6, s63
	v_mov_b32_e32 v0, v232
	s_mov_b32 s4, s2
	s_mov_b32 s5, s3
	s_lshl_b32 s22, s5, 3
	s_abs_i32 s5, s22
	v_cvt_f32_u32_e32 v2, s5
	v_ashrrev_i32_e32 v3, 6, v0
	v_lshl_add_u32 v3, s4, 3, v3
	v_add_u32_e32 v3, 0xfffff3c0, v3
	v_rcp_iflag_f32_e32 v2, v2
	v_sub_u32_e32 v5, 0, v3
	s_sub_i32 s4, 0, s5
	v_ashrrev_i32_e32 v4, 31, v3
	v_mul_f32_e32 v2, 0x4f7ffffe, v2
	v_cvt_u32_f32_e32 v2, v2
	v_max_i32_e32 v3, v3, v5
	v_mul_lo_u32 v5, s4, v2
	v_mul_hi_u32 v5, v2, v5
	v_add_u32_e32 v2, v2, v5
	v_mul_hi_u32 v5, v3, v2
	v_mul_lo_u32 v5, v5, s5
	v_sub_u32_e32 v3, v3, v5
	v_subrev_u32_e32 v5, s5, v3
	v_cmp_le_u32_e32 vcc, s5, v3
	s_movk_i32 s4, 0x300
	s_nop 0
	v_cndmask_b32_e32 v3, v3, v5, vcc
	v_subrev_u32_e32 v5, s5, v3
	v_cmp_le_u32_e32 vcc, s5, v3
	s_nop 1
	v_cndmask_b32_e32 v3, v3, v5, vcc
	v_xor_b32_e32 v3, v3, v4
	v_sub_u32_e32 v3, v3, v4
	v_add_u32_e32 v3, s22, v3
	v_sub_u32_e32 v5, 0, v3
	v_ashrrev_i32_e32 v4, 31, v3
	v_max_i32_e32 v3, v3, v5
	v_mul_hi_u32 v2, v3, v2
	v_mul_lo_u32 v2, v2, s5
	v_sub_u32_e32 v2, v3, v2
	v_subrev_u32_e32 v3, s5, v2
	v_cmp_le_u32_e32 vcc, s5, v2
	s_nop 1
	v_cndmask_b32_e32 v2, v2, v3, vcc
	v_subrev_u32_e32 v3, s5, v2
	v_cmp_le_u32_e32 vcc, s5, v2
	s_nop 1
	v_cndmask_b32_e32 v2, v2, v3, vcc
	v_xor_b32_e32 v2, v2, v4
	v_sub_u32_e32 v22, v2, v4
	v_cmp_gt_i32_e32 vcc, s4, v22
	s_and_saveexec_b64 s[4:5], vcc
	v_readlane_b32 s56, v255, 16
	v_readlane_b32 s57, v255, 17
	s_movk_i32 s59, 0x1ff
	s_cbranch_execz .LBB0_708
	s_ashr_i32 s7, s6, 31
	s_add_u32 s8, s92, s6
	s_addc_u32 s9, s93, s7
	s_lshl_b64 s[10:11], s[6:7], 2
	s_add_u32 s6, s20, s10
	s_addc_u32 s7, s21, s11
	s_add_u32 s8, s8, 0x1c80000
	s_addc_u32 s9, s9, 0
	s_add_u32 s10, s14, s10
	s_addc_u32 s11, s15, s11
	v_lshlrev_b32_e32 v0, 2, v0
	s_add_u32 s10, s10, 0x3c40
	v_and_b32_e32 v23, 0xfc, v0
	s_addc_u32 s11, s11, 0
	v_lshlrev_b32_e32 v24, 4, v22
	s_lshl_b32 s20, s22, 4
	s_mov_b64 s[12:13], 0
	s_branch .LBB0_705
